# nt only on read-once loads (prep weights, x, rms, sample state, final); stores back to default policy
# speedup vs baseline: 1.0143x; 1.0072x over previous
.LBB0_1286:
	v_ashrrev_i32_e32 v33, 31, v32
	v_lshlrev_b64 v[40:41], 7, v[32:33]
	v_lshl_add_u64 v[40:41], v[34:35], 0, v[40:41]
	v_lshlrev_b64 v[46:47], 11, v[32:33]
	global_load_dwordx2 v[62:63], v[40:41], off nt
	v_lshl_add_u64 v[40:41], v[38:39], 0, v[46:47]
	global_load_dwordx4 v[46:49], v[40:41], off nt
	global_load_dwordx4 v[50:53], v[40:41], off offset:1024 nt
	v_add_u32_e32 v40, 1, v32
	v_ashrrev_i32_e32 v41, 31, v40
	v_lshlrev_b64 v[54:55], 7, v[40:41]
	v_lshl_add_u64 v[54:55], v[34:35], 0, v[54:55]
	global_load_dwordx2 v[64:65], v[54:55], off nt
	v_lshlrev_b64 v[56:57], 11, v[40:41]
	v_lshl_add_u64 v[58:59], v[38:39], 0, v[56:57]
	global_load_dwordx4 v[54:57], v[58:59], off nt
	v_lshlrev_b64 v[60:61], 12, v[32:33]
	v_lshl_add_u64 v[70:71], v[36:37], 0, v[60:61]
	global_load_dwordx4 v[58:61], v[58:59], off offset:1024 nt
	v_lshlrev_b64 v[40:41], 12, v[40:41]
	v_lshl_add_u64 v[40:41], v[36:37], 0, v[40:41]
	v_add_u32_e32 v32, s95, v32
	s_waitcnt vmcnt(0)
	ds_bpermute_b32 v66, v42, v62
	ds_bpermute_b32 v67, v42, v63
	v_lshlrev_b32_e32 v33, 16, v46
	v_and_b32_e32 v68, 0xffff0000, v46
	v_lshlrev_b32_e32 v69, 16, v47
	v_and_b32_e32 v72, 0xffff0000, v47
	v_lshlrev_b32_e32 v73, 16, v48
	ds_bpermute_b32 v46, v42, v64
	ds_bpermute_b32 v47, v42, v65
	v_and_b32_e32 v74, 0xffff0000, v48
	v_lshlrev_b32_e32 v75, 16, v49
	v_and_b32_e32 v76, 0xffff0000, v49
	s_waitcnt lgkmcnt(2)
	v_pk_add_f32 v[48:49], v[62:63], v[66:67]
	v_lshlrev_b32_e32 v77, 16, v50
	v_and_b32_e32 v78, 0xffff0000, v50
	v_lshlrev_b32_e32 v79, 16, v51
	v_and_b32_e32 v80, 0xffff0000, v51
	ds_bpermute_b32 v50, v43, v48
	ds_bpermute_b32 v51, v43, v49
	s_waitcnt lgkmcnt(2)
	v_pk_add_f32 v[46:47], v[64:65], v[46:47]
	v_lshlrev_b32_e32 v81, 16, v52
	v_and_b32_e32 v82, 0xffff0000, v52
	v_lshlrev_b32_e32 v83, 16, v53
	v_and_b32_e32 v84, 0xffff0000, v53
	ds_bpermute_b32 v52, v43, v46
	ds_bpermute_b32 v53, v43, v47
	s_waitcnt lgkmcnt(2)
	v_pk_add_f32 v[48:49], v[48:49], v[50:51]
	ds_bpermute_b32 v50, v44, v48
	ds_bpermute_b32 v51, v44, v49
	v_lshlrev_b32_e32 v89, 16, v56
	s_waitcnt lgkmcnt(2)
	v_pk_add_f32 v[46:47], v[46:47], v[52:53]
	ds_bpermute_b32 v52, v44, v46
	ds_bpermute_b32 v53, v44, v47
	s_waitcnt lgkmcnt(2)
	v_pk_add_f32 v[48:49], v[48:49], v[50:51]
	ds_bpermute_b32 v50, v45, v48
	ds_bpermute_b32 v51, v45, v49
	v_and_b32_e32 v90, 0xffff0000, v56
	s_waitcnt lgkmcnt(2)
	v_pk_add_f32 v[46:47], v[46:47], v[52:53]
	ds_bpermute_b32 v52, v45, v46
	ds_bpermute_b32 v53, v45, v47
	s_waitcnt lgkmcnt(2)
	v_pk_add_f32 v[48:49], v[48:49], v[50:51]
	v_lshlrev_b32_e32 v85, 16, v54
	v_pk_mul_f32 v[48:49], v[48:49], s[4:5] op_sel_hi:[1,0]
	v_and_b32_e32 v86, 0xffff0000, v54
	s_waitcnt lgkmcnt(0)
	v_pk_add_f32 v[46:47], v[46:47], v[52:53]
	v_fma_f32 v56, -v48, v48, v49
	v_sub_f32_e32 v51, v72, v48
	v_sub_f32_e32 v52, v33, v48
	v_sub_f32_e32 v62, v73, v48
	v_pk_mul_f32 v[72:73], v[46:47], s[4:5] op_sel_hi:[1,0]
	v_max_f32_e32 v33, 0, v56
	v_fma_f32 v46, -v72, v72, v73
	v_add_f32_e32 v33, 0x3727c5ac, v33
	v_max_f32_e32 v46, 0, v46
	v_mul_f32_e32 v47, 0x4b800000, v33
	v_cmp_gt_f32_e32 vcc, s5, v33
	v_add_f32_e32 v46, 0x3727c5ac, v46
	v_cmp_gt_f32_e64 s[0:1], s5, v46
	v_cndmask_b32_e32 v33, v33, v47, vcc
	v_mul_f32_e32 v47, 0x4b800000, v46
	v_rsq_f32_e32 v33, v33
	v_cndmask_b32_e64 v46, v46, v47, s[0:1]
	v_rsq_f32_e32 v47, v46
	v_sub_f32_e32 v50, v69, v48
	v_mul_f32_e32 v46, 0x45800000, v33
	v_sub_f32_e32 v53, v68, v48
	v_cndmask_b32_e32 v46, v33, v46, vcc
	v_lshlrev_b32_e32 v87, 16, v55
	v_and_b32_e32 v88, 0xffff0000, v55
	v_sub_f32_e32 v55, v76, v48
	v_sub_f32_e32 v54, v75, v48
	v_sub_f32_e32 v63, v74, v48
	v_sub_f32_e32 v65, v80, v48
	v_sub_f32_e32 v64, v79, v48
	v_sub_f32_e32 v67, v78, v48
	v_sub_f32_e32 v66, v77, v48
	v_sub_f32_e32 v69, v84, v48
	v_sub_f32_e32 v68, v83, v48
	v_sub_f32_e32 v49, v82, v48
	v_sub_f32_e32 v48, v81, v48
	v_mul_f32_e32 v33, 0x45800000, v47
	v_pk_mul_f32 v[52:53], v[52:53], v[46:47] op_sel_hi:[1,0]
	v_pk_mul_f32 v[50:51], v[50:51], v[46:47] op_sel_hi:[1,0]
	v_pk_mul_f32 v[62:63], v[62:63], v[46:47] op_sel_hi:[1,0]
	v_pk_mul_f32 v[54:55], v[54:55], v[46:47] op_sel_hi:[1,0]
	v_pk_mul_f32 v[66:67], v[66:67], v[46:47] op_sel_hi:[1,0]
	v_pk_mul_f32 v[64:65], v[64:65], v[46:47] op_sel_hi:[1,0]
	v_pk_mul_f32 v[74:75], v[48:49], v[46:47] op_sel_hi:[1,0]
	v_pk_mul_f32 v[68:69], v[68:69], v[46:47] op_sel_hi:[1,0]
	v_cndmask_b32_e64 v56, v47, v33, s[0:1]
	v_pk_fma_f32 v[48:49], v[2:3], v[50:51], v[18:19]
	v_pk_fma_f32 v[46:47], v[0:1], v[52:53], v[16:17]
	v_lshlrev_b32_e32 v91, 16, v57
	v_pk_fma_f32 v[52:53], v[6:7], v[54:55], v[22:23]
	v_pk_fma_f32 v[50:51], v[4:5], v[62:63], v[20:21]
	v_pk_fma_f32 v[64:65], v[10:11], v[64:65], v[26:27]
	v_pk_fma_f32 v[62:63], v[8:9], v[66:67], v[24:25]
	v_pk_fma_f32 v[68:69], v[14:15], v[68:69], v[30:31]
	v_pk_fma_f32 v[66:67], v[12:13], v[74:75], v[28:29]
	global_store_dwordx4 v[70:71], v[46:49], off
	global_store_dwordx4 v[70:71], v[50:53], off offset:16
	global_store_dwordx4 v[70:71], v[62:65], off offset:2048
	global_store_dwordx4 v[70:71], v[66:69], off offset:2064
	v_and_b32_e32 v33, 0xffff0000, v57
	v_lshlrev_b32_e32 v57, 16, v60
	v_sub_f32_e32 v47, v88, v72
	v_sub_f32_e32 v46, v87, v72
	v_sub_f32_e32 v49, v86, v72
	v_sub_f32_e32 v48, v85, v72
	v_pk_mul_f32 v[50:51], v[48:49], v[56:57] op_sel_hi:[1,0]
	v_pk_mul_f32 v[46:47], v[46:47], v[56:57] op_sel_hi:[1,0]
	v_lshlrev_b32_e32 v52, 16, v58
	v_pk_fma_f32 v[48:49], v[2:3], v[46:47], v[18:19]
	v_pk_fma_f32 v[46:47], v[0:1], v[50:51], v[16:17]
	global_store_dwordx4 v[40:41], v[46:49], off
	v_and_b32_e32 v53, 0xffff0000, v58
	v_lshlrev_b32_e32 v54, 16, v59
	v_sub_f32_e32 v47, v33, v72
	v_sub_f32_e32 v46, v91, v72
	v_sub_f32_e32 v49, v90, v72
	v_sub_f32_e32 v48, v89, v72
	v_pk_mul_f32 v[50:51], v[48:49], v[56:57] op_sel_hi:[1,0]
	v_pk_mul_f32 v[46:47], v[46:47], v[56:57] op_sel_hi:[1,0]
	v_and_b32_e32 v55, 0xffff0000, v59
	v_pk_fma_f32 v[48:49], v[6:7], v[46:47], v[22:23]
	v_pk_fma_f32 v[46:47], v[4:5], v[50:51], v[20:21]
	global_store_dwordx4 v[40:41], v[46:49], off offset:16
	v_and_b32_e32 v58, 0xffff0000, v60
	v_lshlrev_b32_e32 v59, 16, v61
	v_sub_f32_e32 v47, v55, v72
	v_sub_f32_e32 v46, v54, v72
	v_sub_f32_e32 v49, v53, v72
	v_sub_f32_e32 v48, v52, v72
	v_pk_mul_f32 v[50:51], v[48:49], v[56:57] op_sel_hi:[1,0]
	v_pk_mul_f32 v[46:47], v[46:47], v[56:57] op_sel_hi:[1,0]
	v_and_b32_e32 v60, 0xffff0000, v61
	v_pk_fma_f32 v[48:49], v[10:11], v[46:47], v[26:27]
	v_pk_fma_f32 v[46:47], v[8:9], v[50:51], v[24:25]
	global_store_dwordx4 v[40:41], v[46:49], off offset:2048
	v_cmp_lt_i32_e32 vcc, s6, v32
	s_or_b64 s[2:3], vcc, s[2:3]
	v_sub_f32_e32 v47, v60, v72
	v_sub_f32_e32 v46, v59, v72
	v_sub_f32_e32 v49, v58, v72
	v_sub_f32_e32 v48, v57, v72
	v_pk_mul_f32 v[50:51], v[48:49], v[56:57] op_sel_hi:[1,0]
	v_pk_mul_f32 v[46:47], v[46:47], v[56:57] op_sel_hi:[1,0]
	s_nop 0
	v_pk_fma_f32 v[48:49], v[14:15], v[46:47], v[30:31]
	v_pk_fma_f32 v[46:47], v[12:13], v[50:51], v[28:29]
	global_store_dwordx4 v[40:41], v[46:49], off offset:2064
	s_andn2_b64 exec, exec, s[2:3]
	s_cbranch_execnz .LBB0_1286
